# adds: s3 gate-norm tail loads all ssm_norm vectors up front with counted waits; d_skip read as a scalar load issued at the head of each head iteration
# speedup vs baseline: 1.0006x; 1.0006x over previous
.LBB0_133:
	v_readlane_b32 s2, v254, 13
	s_cmp_gt_i32 s2, 5
	s_mov_b64 s[4:5], -1
	s_cbranch_scc0 .LBB0_299
	v_readlane_b32 s4, v252, 31
	v_readlane_b32 s5, v252, 32
	s_andn2_b64 vcc, exec, s[4:5]
	s_cbranch_vccnz .LBB0_298
	v_readlane_b32 s4, v253, 46
	v_readlane_b32 s6, v253, 48
	v_readlane_b32 s5, v253, 47
	v_readlane_b32 s7, v253, 49
	s_add_u32 s4, s6, 0x141e0440
	s_addc_u32 s5, s7, 0
	v_writelane_b32 v254, s4, 20
	v_readlane_b32 s2, v251, 0
	s_mov_b32 s37, s2
	v_writelane_b32 v254, s5, 21
	s_add_u32 s4, s6, 0x90808c0
	s_addc_u32 s5, s7, 0
	v_writelane_b32 v254, s4, 22
	s_nop 1
	v_writelane_b32 v254, s5, 23
	v_readlane_b32 s4, v253, 24
	v_readlane_b32 s5, v253, 25
	s_nop 0
	v_writelane_b32 v254, s4, 24
	s_nop 1
	v_writelane_b32 v254, s5, 25
	s_branch .LBB0_138
	s_nop 0
	s_nop 0
	s_nop 0
	s_nop 0
	s_nop 0
	s_nop 0
	s_nop 0
	s_nop 0
	s_nop 0
	s_nop 0
	s_nop 0
	s_nop 0
.LBB0_136:
	v_readlane_b32 s4, v254, 3
	v_readlane_b32 s5, v254, 4
	s_waitcnt vmcnt(0)
	v_mov_b32_e32 v121, v1
	v_readlane_b32 s6, v253, 59
	v_lshl_add_u64 v[2:3], s[4:5], 0, v[118:119]
	v_readlane_b32 s4, v253, 42
	v_readlane_b32 s5, v253, 43
	s_load_dwordx2 s[4:5], s[4:5], 0xa0
	v_lshl_add_u64 v[4:5], v[2:3], 0, v[120:121]
	s_lshl_b32 s2, s2, 1
	v_readlane_b32 s7, v253, 60
	v_lshl_add_u64 v[4:5], v[4:5], 0, s[2:3]
	s_lshl_b64 s[6:7], s[6:7], 2
	global_load_dwordx4 v[16:19], v[4:5], off offset:1024
	s_waitcnt lgkmcnt(0)
	s_add_u32 s4, s4, s6
	v_lshlrev_b32_e32 v0, 2, v132
	s_addc_u32 s5, s5, s7
	global_load_dwordx4 v[20:23], v0, s[4:5]
	global_load_dwordx4 v[24:27], v0, s[4:5] offset:16
	global_load_dwordx4 v[154:157], v0, s[4:5] offset:128
	global_load_dwordx4 v[158:161], v0, s[4:5] offset:144
	global_load_dwordx4 v[162:165], v0, s[4:5] offset:256
	global_load_dwordx4 v[166:169], v0, s[4:5] offset:272
	global_load_dwordx4 v[170:173], v0, s[4:5] offset:384
	global_load_dwordx4 v[174:177], v0, s[4:5] offset:400
	global_load_dwordx4 v[178:181], v0, s[4:5] offset:512
	global_load_dwordx4 v[182:185], v0, s[4:5] offset:528
	global_load_dwordx4 v[186:189], v0, s[4:5] offset:640
	global_load_dwordx4 v[190:193], v0, s[4:5] offset:656
	global_load_dwordx4 v[202:205], v0, s[4:5] offset:768
	global_load_dwordx4 v[206:209], v0, s[4:5] offset:784
	global_load_dwordx4 v[210:213], v0, s[4:5] offset:896
	global_load_dwordx4 v[214:217], v0, s[4:5] offset:912
	v_and_b32_e32 v7, 64, v243
	v_xor_b32_e32 v6, 16, v243
	v_add_u32_e32 v7, 64, v7
	v_cmp_lt_i32_e32 vcc, v6, v7
	v_xor_b32_e32 v8, 32, v243
	v_mov_b32_e32 v109, v1
	v_cndmask_b32_e32 v6, v243, v6, vcc
	v_lshlrev_b32_e32 v6, 2, v6
	ds_bpermute_b32 v6, v6, v144
	v_cmp_lt_i32_e32 vcc, v8, v7
	v_lshl_add_u64 v[14:15], v[2:3], 0, v[108:109]
	s_mov_b32 s2, 0x800000
	v_cndmask_b32_e32 v7, v243, v8, vcc
	v_lshlrev_b32_e32 v7, 2, v7
	s_waitcnt lgkmcnt(0)
	v_add_f32_e32 v6, v144, v6
	ds_bpermute_b32 v7, v7, v6
	global_load_dwordx4 v[28:31], v[4:5], off offset:1088
	global_load_dwordx4 v[32:35], v[4:5], off offset:1152
	global_load_dwordx4 v[36:39], v[4:5], off offset:1216
	s_waitcnt lgkmcnt(0)
	v_add_f32_e32 v2, v6, v7
	v_fmamk_f32 v2, v2, 0x3b800000, v241
	v_mul_f32_e32 v3, 0x4b800000, v2
	v_cmp_gt_f32_e32 vcc, s2, v2
	s_waitcnt vmcnt(19)
	v_lshlrev_b32_e32 v46, 16, v17
	v_cndmask_b32_e32 v2, v2, v3, vcc
	v_rsq_f32_e32 v44, v2
	v_and_b32_e32 v17, 0xffff0000, v17
	v_lshlrev_b32_e32 v47, 16, v18
	v_and_b32_e32 v18, 0xffff0000, v18
	v_mul_f32_e32 v45, 0x45800000, v44
	v_cndmask_b32_e32 v44, v44, v45, vcc
	v_lshlrev_b32_e32 v45, 16, v16
	v_and_b32_e32 v16, 0xffff0000, v16
	v_lshlrev_b32_e32 v48, 16, v19
	v_and_b32_e32 v19, 0xffff0000, v19
	v_mul_f32_e32 v16, v44, v16
	v_mul_f32_e32 v17, v44, v17
	v_mul_f32_e32 v18, v44, v18
	v_mul_f32_e32 v19, v44, v19
	v_mul_f32_e32 v45, v44, v45
	v_mul_f32_e32 v46, v44, v46
	v_mul_f32_e32 v47, v44, v47
	v_mul_f32_e32 v48, v44, v48
	s_waitcnt vmcnt(18)
	v_mul_f32_e32 v16, v16, v21
	v_mul_f32_e32 v17, v17, v23
	s_waitcnt vmcnt(17)
	v_mul_f32_e32 v18, v18, v25
	v_mul_f32_e32 v19, v19, v27
	global_load_dwordx4 v[40:43], v[4:5], off offset:1280
	global_load_dwordx4 v[10:13], v[4:5], off offset:1344
	global_load_dwordx4 v[6:9], v[4:5], off offset:1408
	s_nop 0
	global_load_dwordx4 v[2:5], v[4:5], off offset:1472
	v_mul_f32_e32 v20, v45, v20
	v_mul_f32_e32 v21, v46, v22
	v_mul_f32_e32 v22, v47, v24
	v_mul_f32_e32 v23, v48, v26
	v_cvt_pk_bf16_f32 v16, v20, v16
	v_cvt_pk_bf16_f32 v17, v21, v17
	v_cvt_pk_bf16_f32 v18, v22, v18
	v_cvt_pk_bf16_f32 v19, v23, v19
	global_store_dwordx4 v[14:15], v[16:19], off offset:1024
	s_nop 0
	s_waitcnt vmcnt(7)
	v_mov_b64_e32 v[16:17], v[154:155]
	v_mov_b64_e32 v[18:19], v[156:157]
	v_mov_b64_e32 v[20:21], v[158:159]
	v_mov_b64_e32 v[22:23], v[160:161]
	v_lshlrev_b32_e32 v24, 16, v28
	v_and_b32_e32 v25, 0xffff0000, v28
	v_lshlrev_b32_e32 v26, 16, v29
	v_and_b32_e32 v27, 0xffff0000, v29
	v_lshlrev_b32_e32 v28, 16, v30
	v_and_b32_e32 v29, 0xffff0000, v30
	v_lshlrev_b32_e32 v30, 16, v31
	v_and_b32_e32 v31, 0xffff0000, v31
	v_mul_f32_e32 v24, v44, v24
	v_mul_f32_e32 v25, v44, v25
	v_mul_f32_e32 v26, v44, v26
	v_mul_f32_e32 v27, v44, v27
	v_mul_f32_e32 v28, v44, v28
	v_mul_f32_e32 v29, v44, v29
	v_mul_f32_e32 v30, v44, v30
	v_mul_f32_e32 v31, v44, v31
	v_mul_f32_e32 v16, v24, v16
	v_mul_f32_e32 v17, v25, v17
	v_mul_f32_e32 v18, v26, v18
	v_mul_f32_e32 v19, v27, v19
	v_mul_f32_e32 v20, v28, v20
	v_mul_f32_e32 v21, v29, v21
	v_mul_f32_e32 v22, v30, v22
	v_mul_f32_e32 v23, v31, v23
	v_cvt_pk_bf16_f32 v16, v16, v17
	v_cvt_pk_bf16_f32 v17, v18, v19
	v_cvt_pk_bf16_f32 v18, v20, v21
	v_cvt_pk_bf16_f32 v19, v22, v23
	global_store_dwordx4 v[14:15], v[16:19], off offset:1088
	s_nop 0
	s_waitcnt vmcnt(7)
	v_mov_b64_e32 v[16:17], v[162:163]
	v_mov_b64_e32 v[18:19], v[164:165]
	v_mov_b64_e32 v[20:21], v[166:167]
	v_mov_b64_e32 v[22:23], v[168:169]
	v_lshlrev_b32_e32 v24, 16, v32
	v_and_b32_e32 v25, 0xffff0000, v32
	v_lshlrev_b32_e32 v26, 16, v33
	v_and_b32_e32 v27, 0xffff0000, v33
	v_lshlrev_b32_e32 v28, 16, v34
	v_and_b32_e32 v29, 0xffff0000, v34
	v_lshlrev_b32_e32 v30, 16, v35
	v_and_b32_e32 v31, 0xffff0000, v35
	v_mul_f32_e32 v24, v44, v24
	v_mul_f32_e32 v25, v44, v25
	v_mul_f32_e32 v26, v44, v26
	v_mul_f32_e32 v27, v44, v27
	v_mul_f32_e32 v28, v44, v28
	v_mul_f32_e32 v29, v44, v29
	v_mul_f32_e32 v30, v44, v30
	v_mul_f32_e32 v31, v44, v31
	v_mul_f32_e32 v16, v24, v16
	v_mul_f32_e32 v17, v25, v17
	v_mul_f32_e32 v18, v26, v18
	v_mul_f32_e32 v19, v27, v19
	v_mul_f32_e32 v20, v28, v20
	v_mul_f32_e32 v21, v29, v21
	v_mul_f32_e32 v22, v30, v22
	v_mul_f32_e32 v23, v31, v23
	v_cvt_pk_bf16_f32 v16, v16, v17
	v_cvt_pk_bf16_f32 v17, v18, v19
	v_cvt_pk_bf16_f32 v18, v20, v21
	v_cvt_pk_bf16_f32 v19, v22, v23
	global_store_dwordx4 v[14:15], v[16:19], off offset:1152
	s_nop 0
	s_waitcnt vmcnt(7)
	v_mov_b64_e32 v[16:17], v[170:171]
	v_mov_b64_e32 v[18:19], v[172:173]
	v_mov_b64_e32 v[20:21], v[174:175]
	v_mov_b64_e32 v[22:23], v[176:177]
	v_lshlrev_b32_e32 v24, 16, v36
	v_and_b32_e32 v25, 0xffff0000, v36
	v_lshlrev_b32_e32 v26, 16, v37
	v_and_b32_e32 v27, 0xffff0000, v37
	v_lshlrev_b32_e32 v28, 16, v38
	v_and_b32_e32 v29, 0xffff0000, v38
	v_lshlrev_b32_e32 v30, 16, v39
	v_and_b32_e32 v31, 0xffff0000, v39
	v_mul_f32_e32 v24, v44, v24
	v_mul_f32_e32 v25, v44, v25
	v_mul_f32_e32 v26, v44, v26
	v_mul_f32_e32 v27, v44, v27
	v_mul_f32_e32 v28, v44, v28
	v_mul_f32_e32 v29, v44, v29
	v_mul_f32_e32 v30, v44, v30
	v_mul_f32_e32 v31, v44, v31
	v_mul_f32_e32 v16, v24, v16
	v_mul_f32_e32 v17, v25, v17
	v_mul_f32_e32 v18, v26, v18
	v_mul_f32_e32 v19, v27, v19
	v_mul_f32_e32 v20, v28, v20
	v_mul_f32_e32 v21, v29, v21
	v_mul_f32_e32 v22, v30, v22
	v_mul_f32_e32 v23, v31, v23
	v_cvt_pk_bf16_f32 v16, v16, v17
	v_cvt_pk_bf16_f32 v17, v18, v19
	v_cvt_pk_bf16_f32 v18, v20, v21
	v_cvt_pk_bf16_f32 v19, v22, v23
	global_store_dwordx4 v[14:15], v[16:19], off offset:1216
	s_nop 0
	s_waitcnt vmcnt(7)
	v_mov_b64_e32 v[16:17], v[178:179]
	v_mov_b64_e32 v[18:19], v[180:181]
	v_mov_b64_e32 v[20:21], v[182:183]
	v_mov_b64_e32 v[22:23], v[184:185]
	v_lshlrev_b32_e32 v24, 16, v40
	v_and_b32_e32 v25, 0xffff0000, v40
	v_lshlrev_b32_e32 v26, 16, v41
	v_and_b32_e32 v27, 0xffff0000, v41
	v_lshlrev_b32_e32 v28, 16, v42
	v_and_b32_e32 v29, 0xffff0000, v42
	v_lshlrev_b32_e32 v30, 16, v43
	v_and_b32_e32 v31, 0xffff0000, v43
	v_mul_f32_e32 v24, v44, v24
	v_mul_f32_e32 v25, v44, v25
	v_mul_f32_e32 v26, v44, v26
	v_mul_f32_e32 v27, v44, v27
	v_mul_f32_e32 v28, v44, v28
	v_mul_f32_e32 v29, v44, v29
	v_mul_f32_e32 v30, v44, v30
	v_mul_f32_e32 v31, v44, v31
	v_mul_f32_e32 v16, v24, v16
	v_mul_f32_e32 v17, v25, v17
	v_mul_f32_e32 v18, v26, v18
	v_mul_f32_e32 v19, v27, v19
	v_mul_f32_e32 v20, v28, v20
	v_mul_f32_e32 v21, v29, v21
	v_mul_f32_e32 v22, v30, v22
	v_mul_f32_e32 v23, v31, v23
	v_cvt_pk_bf16_f32 v16, v16, v17
	v_cvt_pk_bf16_f32 v17, v18, v19
	v_cvt_pk_bf16_f32 v18, v20, v21
	v_cvt_pk_bf16_f32 v19, v22, v23
	global_store_dwordx4 v[14:15], v[16:19], off offset:1280
	s_nop 0
	s_waitcnt vmcnt(7)
	v_mov_b64_e32 v[16:17], v[186:187]
	v_mov_b64_e32 v[18:19], v[188:189]
	v_mov_b64_e32 v[20:21], v[190:191]
	v_mov_b64_e32 v[22:23], v[192:193]
	v_lshlrev_b32_e32 v24, 16, v10
	v_and_b32_e32 v10, 0xffff0000, v10
	v_lshlrev_b32_e32 v25, 16, v11
	v_and_b32_e32 v11, 0xffff0000, v11
	v_lshlrev_b32_e32 v26, 16, v12
	v_and_b32_e32 v12, 0xffff0000, v12
	v_lshlrev_b32_e32 v27, 16, v13
	v_and_b32_e32 v13, 0xffff0000, v13
	v_mul_f32_e32 v10, v44, v10
	v_mul_f32_e32 v11, v44, v11
	v_mul_f32_e32 v12, v44, v12
	v_mul_f32_e32 v13, v44, v13
	v_mul_f32_e32 v24, v44, v24
	v_mul_f32_e32 v25, v44, v25
	v_mul_f32_e32 v26, v44, v26
	v_mul_f32_e32 v27, v44, v27
	v_mul_f32_e32 v10, v10, v17
	v_mul_f32_e32 v11, v11, v19
	v_mul_f32_e32 v12, v12, v21
	v_mul_f32_e32 v13, v13, v23
	v_mul_f32_e32 v16, v24, v16
	v_mul_f32_e32 v17, v25, v18
	v_mul_f32_e32 v18, v26, v20
	v_mul_f32_e32 v19, v27, v22
	v_cvt_pk_bf16_f32 v10, v16, v10
	v_cvt_pk_bf16_f32 v11, v17, v11
	v_cvt_pk_bf16_f32 v12, v18, v12
	v_cvt_pk_bf16_f32 v13, v19, v13
	global_store_dwordx4 v[14:15], v[10:13], off offset:1344
	s_nop 0
	s_waitcnt vmcnt(7)
	v_mov_b64_e32 v[10:11], v[202:203]
	v_mov_b64_e32 v[12:13], v[204:205]
	v_mov_b64_e32 v[16:17], v[206:207]
	v_mov_b64_e32 v[18:19], v[208:209]
	v_lshlrev_b32_e32 v20, 16, v6
	v_and_b32_e32 v6, 0xffff0000, v6
	v_lshlrev_b32_e32 v21, 16, v7
	v_and_b32_e32 v7, 0xffff0000, v7
	v_lshlrev_b32_e32 v22, 16, v8
	v_and_b32_e32 v8, 0xffff0000, v8
	v_lshlrev_b32_e32 v23, 16, v9
	v_and_b32_e32 v9, 0xffff0000, v9
	v_mul_f32_e32 v6, v44, v6
	v_mul_f32_e32 v7, v44, v7
	v_mul_f32_e32 v8, v44, v8
	v_mul_f32_e32 v9, v44, v9
	v_mul_f32_e32 v20, v44, v20
	v_mul_f32_e32 v21, v44, v21
	v_mul_f32_e32 v22, v44, v22
	v_mul_f32_e32 v23, v44, v23
	v_mul_f32_e32 v6, v6, v11
	v_mul_f32_e32 v7, v7, v13
	v_mul_f32_e32 v8, v8, v17
	v_mul_f32_e32 v9, v9, v19
	v_mul_f32_e32 v10, v20, v10
	v_mul_f32_e32 v11, v21, v12
	v_mul_f32_e32 v12, v22, v16
	v_mul_f32_e32 v13, v23, v18
	v_cvt_pk_bf16_f32 v6, v10, v6
	v_cvt_pk_bf16_f32 v7, v11, v7
	v_cvt_pk_bf16_f32 v8, v12, v8
	v_cvt_pk_bf16_f32 v9, v13, v9
	global_store_dwordx4 v[14:15], v[6:9], off offset:1408
	s_nop 0
	s_waitcnt vmcnt(7)
	v_mov_b64_e32 v[6:7], v[210:211]
	v_mov_b64_e32 v[8:9], v[212:213]
	v_mov_b64_e32 v[10:11], v[214:215]
	v_mov_b64_e32 v[12:13], v[216:217]
	v_lshlrev_b32_e32 v0, 16, v2
	v_and_b32_e32 v2, 0xffff0000, v2
	v_lshlrev_b32_e32 v16, 16, v3
	v_and_b32_e32 v3, 0xffff0000, v3
	v_lshlrev_b32_e32 v17, 16, v4
	v_and_b32_e32 v4, 0xffff0000, v4
	v_mul_f32_e32 v0, v44, v0
	v_mul_f32_e32 v2, v44, v2
	v_mul_f32_e32 v16, v44, v16
	v_mul_f32_e32 v3, v44, v3
	v_mul_f32_e32 v17, v44, v17
	v_lshlrev_b32_e32 v18, 16, v5
	v_and_b32_e32 v5, 0xffff0000, v5
	v_mul_f32_e32 v4, v44, v4
	s_mov_b64 s[4:5], 0x5c0
	v_mul_f32_e32 v18, v44, v18
	v_mul_f32_e32 v5, v44, v5
	v_mul_f32_e32 v0, v0, v6
	v_mul_f32_e32 v2, v2, v7
	v_mul_f32_e32 v6, v16, v8
	v_mul_f32_e32 v3, v3, v9
	v_mul_f32_e32 v7, v17, v10
	v_mul_f32_e32 v4, v4, v11
	v_cvt_pk_bf16_f32 v0, v0, v2
	v_cvt_pk_bf16_f32 v2, v6, v3
	v_cvt_pk_bf16_f32 v3, v7, v4
	v_lshl_add_u64 v[6:7], v[14:15], 0, s[4:5]
	v_mul_f32_e32 v8, v18, v12
	v_mul_f32_e32 v5, v5, v13
	v_cvt_pk_bf16_f32 v4, v8, v5
	global_store_dword v[14:15], v0, off offset:1472

.LBB0_143:
	s_or_b64 exec, exec, s[6:7]
	v_add_u32_e32 v36, s4, v104
	v_ashrrev_i32_e32 v37, 31, v36
	v_readlane_b32 s12, v253, 46
	v_lshlrev_b64 v[36:37], 11, v[36:37]
	v_readlane_b32 s13, v253, 47
	v_lshlrev_b32_e32 v0, 4, v102
	v_and_b32_e32 v0, 0xf0, v0
	v_lshl_add_u64 v[36:37], s[12:13], 0, v[36:37]
	v_lshl_add_u64 v[36:37], v[36:37], 0, s[2:3]
	v_lshl_add_u64 v[42:43], v[36:37], 0, v[0:1]
	global_load_dwordx4 v[156:159], v[42:43], off offset:1536
	v_readlane_b32 s98, v253, 42
	v_readlane_b32 s99, v253, 43
	global_load_dwordx4 v[160:163], v[42:43], off offset:1024
	v_add_u32_e32 v40, 0, v0
	s_movk_i32 s8, 0x110
	v_mad_u64_u32 v[44:45], s[6:7], v104, s8, v[40:41]
	v_lshlrev_b32_e32 v120, 1, v121
	v_add_u32_e32 v93, 0, v120
	v_cmp_lt_i32_e32 vcc, -1, v100
	v_mad_u32_u24 v95, v101, s8, v93
	v_readlane_b32 s14, v253, 48
	v_readlane_b32 s15, v253, 49
	v_mov_b32_e32 v154, v44
	v_add_u32_e32 v36, s4, v106
	v_ashrrev_i32_e32 v37, 31, v36
	v_lshlrev_b64 v[36:37], 11, v[36:37]
	v_lshl_add_u64 v[36:37], s[12:13], 0, v[36:37]
	v_lshl_add_u64 v[36:37], v[36:37], 0, s[2:3]
	v_lshl_add_u64 v[42:43], v[36:37], 0, v[0:1]
	s_load_dwordx2 s[100:101], s[98:99], 0x98
	global_load_dwordx4 v[164:167], v[42:43], off offset:1536
	global_load_dwordx4 v[168:171], v[42:43], off offset:1024
	v_mad_u64_u32 v[44:45], s[6:7], v106, s8, v[40:41]
	v_ashrrev_i32_e32 v36, 4, v2
	v_add_u32_e32 v2, s4, v36
	v_ashrrev_i32_e32 v3, 31, v2
	v_lshlrev_b64 v[2:3], 11, v[2:3]
	v_lshl_add_u64 v[2:3], s[12:13], 0, v[2:3]
	v_lshl_add_u64 v[2:3], v[2:3], 0, s[2:3]
	v_lshl_add_u64 v[2:3], v[2:3], 0, v[0:1]
	v_mad_u64_u32 v[42:43], s[6:7], v36, s8, v[40:41]
	global_load_dwordx4 v[172:175], v[2:3], off offset:1536
	global_load_dwordx4 v[176:179], v[2:3], off offset:1024
	v_ashrrev_i32_e32 v36, 4, v91
	v_add_u32_e32 v2, s4, v36
	v_ashrrev_i32_e32 v3, 31, v2
	v_lshlrev_b64 v[2:3], 11, v[2:3]
	v_lshl_add_u64 v[2:3], s[12:13], 0, v[2:3]
	v_lshl_add_u64 v[2:3], v[2:3], 0, s[2:3]
	v_lshl_add_u64 v[2:3], v[2:3], 0, v[0:1]
	v_mad_u64_u32 v[40:41], s[4:5], v36, s8, v[40:41]
	global_load_dwordx4 v[180:183], v[2:3], off offset:1536
	global_load_dwordx4 v[184:187], v[2:3], off offset:1024
	v_mul_lo_u32 v0, v80, s8
	v_add_u32_e32 v81, 0, v0
	v_add_u32_e32 v109, v81, v120
	v_mov_b32_e32 v0, v1
	v_mov_b32_e32 v2, v1
	v_mov_b32_e32 v3, v1
	s_waitcnt vmcnt(7)
	ds_write_b128 v154, v[156:159]
	s_waitcnt vmcnt(6)
	ds_write_b128 v154, v[160:163] offset:34816
	s_waitcnt vmcnt(5)
	ds_write_b128 v44, v[164:167]
	s_waitcnt vmcnt(4)
	ds_write_b128 v44, v[168:171] offset:34816
	s_waitcnt vmcnt(3)
	ds_write_b128 v42, v[172:175]
	s_waitcnt vmcnt(2)
	ds_write_b128 v42, v[176:179] offset:34816
	s_waitcnt vmcnt(1)
	ds_write_b128 v40, v[180:183]
	s_waitcnt vmcnt(0)
	ds_write_b128 v40, v[184:187] offset:34816
	s_nop 0
	s_nop 0
	s_nop 0
	s_nop 0
	s_nop 0
	s_nop 0
	s_nop 0
	s_nop 0
	s_nop 0
	s_waitcnt lgkmcnt(0)
	s_barrier
	ds_read_b128 v[76:79], v109
	v_mov_b64_e32 v[38:39], v[2:3]
	v_mov_b64_e32 v[36:37], v[0:1]
	s_and_saveexec_b64 s[4:5], vcc
	s_cbranch_execz .LBB0_145
	ds_read_b128 v[36:39], v95 offset:34816
	s_waitcnt lgkmcnt(0)
	v_mfma_f32_16x16x32_bf16 v[36:39], v[36:39], v[76:79], 0

.LBB0_186:
	s_add_u32 s98, s100, s38
	s_addc_u32 s99, s101, s39
	s_load_dword s98, s[98:99], 0x0
	v_cvt_pk_bf16_f32 v76, v12, v13
	v_cvt_pk_bf16_f32 v77, v14, v15
	ds_write_b16 v136, v4
	ds_write_b16_d16_hi v136, v4 offset:272
	ds_write_b16 v136, v5 offset:544
	ds_write_b16_d16_hi v136, v5 offset:816
	ds_write_b16 v136, v6 offset:4352
	ds_write_b16_d16_hi v136, v6 offset:4624
	ds_write_b16 v136, v7 offset:4896
	ds_write_b16_d16_hi v136, v7 offset:5168
	ds_write_b16 v137, v8
	ds_write_b16_d16_hi v137, v8 offset:272
	ds_write_b16 v137, v9 offset:544
	ds_write_b16_d16_hi v137, v9 offset:816
	ds_write_b16 v137, v10 offset:4352
	ds_write_b16_d16_hi v137, v10 offset:4624
	ds_write_b16 v137, v11 offset:4896
	ds_write_b16_d16_hi v137, v11 offset:5168
	ds_write_b64 v138, v[76:77]
	v_cvt_pk_bf16_f32 v76, v16, v17
	v_cvt_pk_bf16_f32 v77, v18, v19
	ds_write_b64 v139, v[76:77]
	v_cvt_pk_bf16_f32 v76, v20, v21
	v_cvt_pk_bf16_f32 v77, v22, v23
	ds_write_b64 v140, v[76:77]
	v_cvt_pk_bf16_f32 v76, v24, v25
	v_cvt_pk_bf16_f32 v77, v26, v27
	ds_write_b64 v141, v[76:77]
	s_cmpk_eq_i32 s33, 0x600
	v_mov_b64_e32 v[84:85], v[68:69]
	v_mov_b64_e32 v[86:87], v[70:71]
	v_mov_b64_e32 v[88:89], v[28:29]
	v_mov_b64_e32 v[90:91], v[30:31]
	v_mov_b64_e32 v[76:77], v[72:73]
	v_mov_b64_e32 v[78:79], v[74:75]
	v_mov_b64_e32 v[80:81], v[32:33]
	v_mov_b64_e32 v[82:83], v[34:35]
	s_cbranch_scc0 .LBB0_194
	v_add_u32_e32 v0, s33, v135
	ds_read_b32 v0, v0
	s_and_saveexec_b64 s[28:29], vcc
	s_cbranch_execnz .LBB0_195

.LBB0_271:
	s_or_b64 exec, exec, s[28:29]
	v_lshlrev_b32_e32 v145, 16, v72
	v_lshlrev_b32_e32 v147, 16, v68
	v_and_b32_e32 v68, 0xffff0000, v68
	v_and_b32_e32 v72, 0xffff0000, v72
	s_waitcnt lgkmcnt(0)
	v_mov_b32_e32 v0, s98
	v_lshlrev_b32_e32 v148, 16, v69
	v_lshlrev_b32_e32 v146, 16, v73
	v_and_b32_e32 v73, 0xffff0000, v73
	v_and_b32_e32 v69, 0xffff0000, v69
	s_addk_i32 s33, 0x200
	v_fma_f32 v104, v0, v145, v104
	v_mul_f32_e32 v145, 0xbfb8aa3b, v147
	v_exp_f32_e32 v145, v145
	v_fma_f32 v72, v0, v72, v105
	v_fmac_f32_e32 v107, v0, v73
	v_and_b32_e32 v73, 0xffff0000, v70
	v_add_f32_e32 v145, 1.0, v145
	v_rcp_f32_e32 v145, v145
	s_nop 0
	v_mul_f32_e32 v145, v145, v147
	v_mul_f32_e32 v145, v145, v104
	v_mul_f32_e32 v104, 0xbfb8aa3b, v68
	v_exp_f32_e32 v104, v104
	v_fmac_f32_e32 v144, v145, v145
	v_add_f32_e32 v104, 1.0, v104
	v_rcp_f32_e32 v104, v104
	s_nop 0
	v_mul_f32_e32 v68, v104, v68
	v_mul_f32_e32 v147, v68, v72
	v_mul_f32_e32 v72, 0xbfb8aa3b, v148
	v_exp_f32_e32 v72, v72
	v_fma_f32 v68, v0, v146, v106
	v_fmac_f32_e32 v144, v147, v147
	v_add_f32_e32 v72, 1.0, v72
	v_rcp_f32_e32 v72, v72
	s_nop 0
	v_mul_f32_e32 v72, v72, v148
	v_mul_f32_e32 v106, v72, v68
	v_lshlrev_b32_e32 v72, 16, v70
	v_mul_f32_e32 v70, 0xbfb8aa3b, v72
	v_exp_f32_e32 v70, v70
	v_mul_f32_e32 v68, 0xbfb8aa3b, v69
	v_exp_f32_e32 v68, v68
	v_fmac_f32_e32 v144, v106, v106
	v_add_f32_e32 v70, 1.0, v70
	v_rcp_f32_e32 v104, v70
	v_mul_f32_e32 v70, 0xbfb8aa3b, v73
	v_exp_f32_e32 v70, v70
	v_add_f32_e32 v68, 1.0, v68
	v_rcp_f32_e32 v68, v68
	v_add_f32_e32 v70, 1.0, v70
	v_rcp_f32_e32 v105, v70
	v_mul_f32_e32 v68, v68, v69
	v_mul_f32_e32 v107, v68, v107
	v_and_b32_e32 v69, 0xffff0000, v74
	v_lshlrev_b32_e32 v68, 16, v74
	v_pk_fma_f32 v[68:69], v[0:1], v[68:69], v[100:101] op_sel_hi:[0,1,1]
	v_pk_mul_f32 v[72:73], v[104:105], v[72:73]
	v_fmac_f32_e32 v144, v107, v107
	v_pk_mul_f32 v[68:69], v[72:73], v[68:69]
	v_lshlrev_b32_e32 v74, 16, v71
	v_pk_mul_f32 v[72:73], v[68:69], v[68:69]
	s_nop 0
	v_add_f32_e32 v70, v72, v144
	v_add_f32_e32 v100, v73, v70
	v_and_b32_e32 v73, 0xffff0000, v75
	v_lshlrev_b32_e32 v72, 16, v75
	v_and_b32_e32 v75, 0xffff0000, v71
	v_mul_f32_e32 v70, 0xbfb8aa3b, v74
	v_mul_f32_e32 v71, 0xbfb8aa3b, v75
	v_exp_f32_e32 v70, v70
	v_exp_f32_e32 v71, v71
	v_pk_fma_f32 v[72:73], v[0:1], v[72:73], v[102:103] op_sel_hi:[0,1,1]
	v_add_f32_e32 v70, 1.0, v70
	v_add_f32_e32 v71, 1.0, v71
	v_rcp_f32_e32 v70, v70
	v_rcp_f32_e32 v71, v71
	s_nop 0
	v_pk_mul_f32 v[70:71], v[70:71], v[74:75]
	s_nop 0
	v_pk_mul_f32 v[74:75], v[70:71], v[72:73]
	v_cvt_pk_bf16_f32 v72, v68, v69
	v_lshl_add_u64 v[68:69], v[126:127], 0, s[34:35]
	v_pk_mul_f32 v[70:71], v[74:75], v[74:75]
	v_cvt_pk_bf16_f32 v73, v74, v75
	s_add_u32 s34, s34, 0x80
	v_add_f32_e32 v70, v70, v100
	v_add_f32_e32 v100, v71, v70
	v_cvt_pk_bf16_f32 v70, v145, v147
	v_cvt_pk_bf16_f32 v71, v106, v107
	global_store_dwordx4 v[68:69], v[70:73], off offset:-64
	s_addc_u32 s35, s35, 0
	s_add_u32 s38, s38, 4
	v_lshlrev_b32_e32 v70, 16, v28
	v_and_b32_e32 v71, 0xffff0000, v28
	v_mul_f32_e32 v28, 0xbfb8aa3b, v70
	v_exp_f32_e32 v28, v28
	v_and_b32_e32 v73, 0xffff0000, v32
	v_lshlrev_b32_e32 v72, 16, v32
	v_pk_fma_f32 v[72:73], v[0:1], v[72:73], v[96:97] op_sel_hi:[0,1,1]
	v_add_f32_e32 v28, 1.0, v28
	v_rcp_f32_e32 v74, v28
	v_mul_f32_e32 v28, 0xbfb8aa3b, v71
	v_exp_f32_e32 v28, v28
	v_lshlrev_b32_e32 v32, 16, v29
	s_addc_u32 s39, s39, 0
	s_add_i32 s36, s36, 1
	v_add_f32_e32 v28, 1.0, v28
	v_rcp_f32_e32 v75, v28
	s_cmpk_lg_i32 s33, 0x800
	v_pk_mul_f32 v[70:71], v[74:75], v[70:71]
	s_nop 0
	v_pk_mul_f32 v[70:71], v[70:71], v[72:73]
	s_nop 0
	v_pk_mul_f32 v[72:73], v[70:71], v[70:71]
	s_nop 0
	v_add_f32_e32 v28, v72, v100
	v_add_f32_e32 v74, v73, v28
	v_and_b32_e32 v73, 0xffff0000, v33
	v_lshlrev_b32_e32 v72, 16, v33
	v_and_b32_e32 v33, 0xffff0000, v29
	v_mul_f32_e32 v28, 0xbfb8aa3b, v32
	v_mul_f32_e32 v29, 0xbfb8aa3b, v33
	v_exp_f32_e32 v28, v28
	v_exp_f32_e32 v29, v29
	v_pk_fma_f32 v[72:73], v[0:1], v[72:73], v[98:99] op_sel_hi:[0,1,1]
	v_add_f32_e32 v28, 1.0, v28
	v_add_f32_e32 v29, 1.0, v29
	v_rcp_f32_e32 v28, v28
	v_rcp_f32_e32 v29, v29
	s_nop 0
	v_pk_mul_f32 v[28:29], v[28:29], v[32:33]
	s_nop 0
	v_pk_mul_f32 v[32:33], v[28:29], v[72:73]
	v_lshlrev_b32_e32 v72, 16, v30
	v_and_b32_e32 v73, 0xffff0000, v30
	v_mul_f32_e32 v30, 0xbfb8aa3b, v72
	v_exp_f32_e32 v30, v30
	v_pk_mul_f32 v[28:29], v[32:33], v[32:33]
	v_add_f32_e32 v30, 1.0, v30
	v_add_f32_e32 v28, v28, v74
	v_rcp_f32_e32 v74, v30
	v_mul_f32_e32 v30, 0xbfb8aa3b, v73
	v_exp_f32_e32 v30, v30
	v_add_f32_e32 v96, v29, v28
	v_and_b32_e32 v29, 0xffff0000, v34
	v_lshlrev_b32_e32 v28, 16, v34
	v_add_f32_e32 v30, 1.0, v30
	v_rcp_f32_e32 v75, v30
	v_pk_fma_f32 v[28:29], v[0:1], v[28:29], v[92:93] op_sel_hi:[0,1,1]
	v_lshlrev_b32_e32 v34, 16, v31
	v_mul_f32_e32 v30, 0xbfb8aa3b, v34
	v_pk_mul_f32 v[72:73], v[74:75], v[72:73]
	v_exp_f32_e32 v30, v30
	v_pk_mul_f32 v[72:73], v[72:73], v[28:29]
	v_add_f32_e32 v30, 1.0, v30
	v_pk_mul_f32 v[28:29], v[72:73], v[72:73]
	v_rcp_f32_e32 v30, v30
	v_add_f32_e32 v28, v28, v96
	v_add_f32_e32 v74, v29, v28
	v_and_b32_e32 v29, 0xffff0000, v35
	v_lshlrev_b32_e32 v28, 16, v35
	v_and_b32_e32 v35, 0xffff0000, v31
	v_pk_fma_f32 v[28:29], v[0:1], v[28:29], v[94:95] op_sel_hi:[0,1,1]
	v_mul_f32_e32 v0, 0xbfb8aa3b, v35
	v_exp_f32_e32 v0, v0
	s_nop 0
	v_add_f32_e32 v0, 1.0, v0
	v_rcp_f32_e32 v31, v0
	s_nop 0
	v_pk_mul_f32 v[30:31], v[30:31], v[34:35]
	s_nop 0
	v_pk_mul_f32 v[34:35], v[30:31], v[28:29]
	v_cvt_pk_bf16_f32 v30, v72, v73
	s_nop 0
	v_pk_mul_f32 v[28:29], v[34:35], v[34:35]
	v_cvt_pk_bf16_f32 v31, v34, v35
	s_nop 0
	v_add_f32_e32 v0, v28, v74
	v_add_f32_e32 v144, v29, v0
	v_cvt_pk_bf16_f32 v28, v70, v71
	v_cvt_pk_bf16_f32 v29, v32, v33
	global_store_dwordx4 v[68:69], v[28:31], off
	s_waitcnt lgkmcnt(0)
	s_barrier
	s_cbranch_scc0 .LBB0_136
	s_waitcnt vmcnt(2)
	v_mov_b64_e32 v[68:69], v[84:85]
	v_mov_b64_e32 v[70:71], v[86:87]
	v_mov_b64_e32 v[28:29], v[88:89]
	v_mov_b64_e32 v[30:31], v[90:91]
	v_mov_b64_e32 v[72:73], v[76:77]
	v_mov_b64_e32 v[74:75], v[78:79]
	v_mov_b64_e32 v[32:33], v[80:81]
	v_mov_b64_e32 v[34:35], v[82:83]
	s_branch .LBB0_186
	s_nop 0
	s_nop 0
	s_nop 0
	s_nop 0
	s_nop 0
